# SSD item: one static s_setprio 1 for the younger half (waves 4-7), reset after the SSD loop
# speedup vs baseline: 1.0102x; 1.0027x over previous
.LBB0_347:
	s_or_b64 exec, exec, s[0:1]
	v_mul_f32_e32 v4, 0x3fb8aa3b, v4
	v_exp_f32_e32 v63, v4
	v_cmp_gt_i32_e64 s[38:39], s35, v1
	v_add_u32_e32 v4, 0xffffff00, v1
	v_mov_b32_e32 v5, 0x1000
	v_cndmask_b32_e64 v51, v4, v1, s[38:39]
	v_mov_b32_e32 v4, 0x1200
	s_lshl_b32 s0, s36, 4
	v_cndmask_b32_e64 v4, v4, v5, s[38:39]
	s_and_b32 s0, s0, 0x180
	v_ashrrev_i32_e32 v48, 4, v51
	v_or_b32_e32 v54, s0, v4
	v_lshlrev_b32_e32 v4, 3, v51
	s_movk_i32 s0, 0x78
	s_lshl_b32 s23, s36, 6
	s_lshl_b32 s85, s37, 12
	v_and_or_b32 v4, v4, s0, v54
	s_bitset1_b32 s23, 11
	v_lshlrev_b32_e32 v50, 2, v48
	s_add_i32 s70, s85, -16
	v_and_or_b32 v20, v2, 60, s23
	v_subrev_u32_e32 v5, 48, v50
	v_lshlrev_b32_e32 v2, 1, v4
	v_cmp_lt_i32_e32 vcc, 15, v48
	v_mov_b32_e32 v52, s70
	v_lshl_add_u64 v[22:23], s[96:97], 0, v[2:3]
	v_max_i32_e32 v2, 0, v5
	v_cndmask_b32_e32 v4, v229, v52, vcc
	v_add_u32_e32 v2, v2, v4
	v_mad_i64_i32 v[4:5], s[0:1], v2, s29, v[22:23]
	v_subrev_u32_e32 v2, 47, v50
	v_cmp_lt_i32_e32 vcc, 15, v2
	v_max_i32_e32 v8, 0, v2
	v_ashrrev_i32_e32 v49, 4, v1
	v_cndmask_b32_e32 v2, v229, v52, vcc
	v_add_u32_e32 v2, v2, v8
	v_mad_i64_i32 v[8:9], s[26:27], v2, s29, v[22:23]
	v_subrev_u32_e32 v2, 46, v50
	v_cmp_lt_i32_e32 vcc, 15, v2
	v_max_i32_e32 v12, 0, v2
	v_lshlrev_b32_e32 v55, 1, v49
	v_cndmask_b32_e32 v2, v229, v52, vcc
	v_add_u32_e32 v2, v2, v12
	v_mad_i64_i32 v[12:13], s[26:27], v2, s29, v[22:23]
	v_subrev_u32_e32 v2, 45, v50
	v_cmp_lt_i32_e32 vcc, 15, v2
	v_max_i32_e32 v16, 0, v2
	v_subrev_u32_e32 v21, 48, v55
	v_cndmask_b32_e32 v2, v229, v52, vcc
	v_add_u32_e32 v2, v2, v16
	v_mad_i64_i32 v[16:17], s[26:27], v2, s29, v[22:23]
	v_lshlrev_b32_e32 v2, 1, v20
	v_cmp_lt_i32_e32 vcc, 31, v49
	v_lshl_add_u64 v[46:47], s[96:97], 0, v[2:3]
	v_max_i32_e32 v2, 0, v21
	v_cndmask_b32_e32 v20, v229, v52, vcc
	v_add_u32_e32 v2, v2, v20
	v_mad_i64_i32 v[20:21], s[26:27], v2, s29, v[46:47]
	v_subrev_u32_e32 v2, 47, v55
	v_cmp_lt_i32_e32 vcc, 15, v2
	global_load_dwordx2 v[40:41], v[20:21], off
	v_max_i32_e32 v20, 0, v2
	v_cndmask_b32_e32 v2, v229, v52, vcc
	v_and_b32_e32 v65, 63, v1
	v_add_u32_e32 v2, v2, v20
	v_mad_i64_i32 v[20:21], s[26:27], v2, s29, v[46:47]
	v_max_u32_e32 v2, 48, v65
	v_readlane_b32 s42, v252, 52
	v_lshlrev_b32_e32 v2, 7, v2
	v_readlane_b32 s43, v252, 53
	global_load_dwordx2 v[42:43], v[20:21], off
	s_mov_b32 s24, 0x3fe000
	v_lshl_add_u64 v[20:21], s[42:43], 0, v[2:3]
	v_lshl_add_u64 v[20:21], v[20:21], 0, s[72:73]
	v_add_co_u32_e32 v20, vcc, s24, v20
	v_add_u32_e32 v2, 16, v50
	s_nop 0
	v_addc_co_u32_e32 v21, vcc, 0, v21, vcc
	v_cmp_lt_i32_e32 vcc, -1, v48
	global_load_dword v20, v[20:21], off offset:2048
	v_max_i32_e32 v2, 0, v2
	v_cndmask_b32_e32 v21, v229, v52, vcc
	v_add_u32_e32 v2, v2, v21
	v_mad_i64_i32 v[24:25], s[26:27], v2, s29, v[22:23]
	v_add_u32_e32 v2, 17, v50
	v_cmp_lt_i32_e32 vcc, 15, v2
	v_max_i32_e32 v21, 0, v2
	global_load_dwordx4 v[24:27], v[24:25], off
	v_cndmask_b32_e32 v2, v229, v52, vcc
	v_add_u32_e32 v2, v2, v21
	v_mad_i64_i32 v[28:29], s[26:27], v2, s29, v[22:23]
	v_add_u32_e32 v2, 18, v50
	v_cmp_lt_i32_e32 vcc, 15, v2
	v_max_i32_e32 v21, 0, v2
	s_ashr_i32 s21, s25, 8
	v_cndmask_b32_e32 v2, v229, v52, vcc
	v_add_u32_e32 v2, v2, v21
	v_mad_i64_i32 v[32:33], s[26:27], v2, s29, v[22:23]
	v_add_u32_e32 v2, 19, v50
	v_cmp_lt_i32_e32 vcc, 15, v2
	v_max_i32_e32 v21, 0, v2
	global_load_dwordx4 v[28:31], v[28:29], off
	v_cndmask_b32_e32 v2, v229, v52, vcc
	v_add_u32_e32 v2, v2, v21
	v_mad_i64_i32 v[22:23], s[26:27], v2, s29, v[22:23]
	v_add_u32_e32 v2, 16, v55
	v_cmp_lt_i32_e32 vcc, -1, v49
	v_max_i32_e32 v2, 0, v2
	global_load_dwordx4 v[36:39], v[22:23], off
	v_cndmask_b32_e32 v21, v229, v52, vcc
	v_add_u32_e32 v2, v2, v21
	v_mad_i64_i32 v[22:23], s[26:27], v2, s29, v[46:47]
	v_add_u32_e32 v2, 17, v55
	v_cmp_lt_i32_e32 vcc, 15, v2
	v_max_i32_e32 v21, 0, v2
	global_load_dwordx2 v[44:45], v[22:23], off
	v_cndmask_b32_e32 v2, v229, v52, vcc
	v_add_u32_e32 v2, v2, v21
	v_mad_i64_i32 v[22:23], s[26:27], v2, s29, v[46:47]
	v_or_b32_e32 v56, s85, v65
	s_lshr_b32 s22, s25, 6
	s_bfe_u32 s20, s25, 0x20006
	v_ashrrev_i32_e32 v57, 31, v56
	s_lshl_b32 s24, s21, 5
	s_sub_i32 s37, s85, 64
	s_lshl_b32 s26, s36, 7
	global_load_dwordx4 v[32:35], v[32:33], off
	s_add_u32 s36, s96, s26
	global_load_dwordx2 v[46:47], v[22:23], off
	v_lshlrev_b64 v[22:23], 7, v[56:57]
	v_and_b32_e32 v94, 15, v1
	v_lshl_add_u64 v[22:23], s[42:43], 0, v[22:23]
	s_addc_u32 s42, s97, 0
	s_lshl_b32 s27, s20, 4
	s_lshl_b32 s26, s20, 5
	v_or_b32_e32 v86, s24, v94
	s_add_u32 s74, s36, s26
	v_lshrrev_b32_e32 v2, 1, v1
	v_lshl_add_u64 v[22:23], v[22:23], 0, s[72:73]
	s_addc_u32 s75, s42, 0
	v_and_b32_e32 v2, 24, v2
	v_cmp_lt_i32_e32 vcc, 63, v86
	v_mov_b32_e32 v21, s37
	global_load_dword v57, v[22:23], off
	v_lshl_add_u64 v[22:23], s[74:75], 0, v[2:3]
	v_max_i32_e32 v2, 48, v86
	v_cndmask_b32_e32 v52, v230, v21, vcc
	v_or_b32_e32 v87, 16, v86
	v_add_u32_e32 v2, v52, v2
	v_cmp_lt_i32_e32 vcc, 63, v87
	v_mad_i64_i32 v[52:53], s[36:37], v2, s29, v[22:23]
	v_max_i32_e32 v2, 48, v87
	v_cndmask_b32_e32 v21, v230, v21, vcc
	v_add_u32_e32 v2, v21, v2
	v_mad_i64_i32 v[22:23], s[36:37], v2, s29, v[22:23]
	global_load_dwordx4 v[4:7], v[4:5], off
	s_cmp_lt_u32 s25, 64
	global_load_dwordx4 v[8:11], v[8:9], off
	s_cselect_b64 s[60:61], -1, 0
	s_cmp_lt_u32 s25, 0x100
	s_cbranch_scc1 .Lssd_noprio
	s_setprio 1
.Lssd_noprio:
	global_load_dwordx4 v[12:15], v[12:13], off
	v_cmp_lt_i32_e64 s[0:1], 11, v48
	global_load_dwordx4 v[16:19], v[16:17], off
	v_cmp_lt_i32_e64 s[40:41], 23, v49
	global_load_dwordx2 v[52:53], v[52:53], off
	s_and_b64 vcc, exec, s[60:61]
	global_load_dwordx2 v[84:85], v[22:23], off
	s_waitcnt lgkmcnt(0)
	s_barrier
	s_cbranch_vccz .LBB0_349
	v_cmp_lt_u32_e32 vcc, 47, v65
	v_mov_b32_e32 v21, v3
	s_waitcnt vmcnt(13)
	v_cndmask_b32_e32 v2, 0, v20, vcc
	v_mul_f32_e64 v20, v2, -v63
	s_nop 1
	v_mov_b32_dpp v21, v20 row_shr:1 row_mask:0xf bank_mask:0xf
	v_fma_f32 v20, v2, -v63, v21
	v_mov_b32_e32 v21, v3
	s_nop 0
	v_add_f32_dpp v20, v20, v20 row_shr:2 row_mask:0xf bank_mask:0xf bound_ctrl:1
	s_nop 1
	v_add_f32_dpp v20, v20, v20 row_shr:4 row_mask:0xf bank_mask:0xf bound_ctrl:1
	s_nop 1
	v_add_f32_dpp v20, v20, v20 row_shr:8 row_mask:0xf bank_mask:0xf bound_ctrl:1
	s_nop 1
	v_mov_b32_dpp v21, v20 row_bcast:15 row_mask:0xa bank_mask:0xf
	v_add_f32_e32 v20, v20, v21
	v_mov_b32_e32 v21, v3
	s_nop 1
	v_mov_b32_dpp v21, v20 row_bcast:31 row_mask:0xc bank_mask:0xf
	v_add_f32_e32 v20, v20, v21
	v_lshl_add_u32 v21, v65, 2, 0
	v_add_u32_e32 v22, 0x1a400, v21
	ds_write_b32 v22, v2
	v_add_u32_e32 v2, 0x1a600, v21
	ds_write_b32 v2, v20

.LBB0_377:
	s_setprio 0
	s_cmpk_gt_i32 s80, 0x41f
	s_cbranch_scc0 .LBB0_392
